# FF2 stream-K: workgroups of one XCD take consecutive stream positions and prompt tiles are enumerated column-tile-major, so an XCD's workgroups share one W_ff2 column tile in L2
# speedup vs baseline: 1.0097x; 1.0074x over previous
.LBB0_411:
	s_or_b64 exec, exec, s[0:1]
	s_cmpk_lt_i32 s2, 0x330
	s_mul_hi_i32 s0, s2, 0xa0a0a0a1
	s_cselect_b64 s[26:27], -1, 0
	s_add_i32 s0, s0, s2
	s_lshr_b32 s1, s0, 31
	s_lshr_b32 s0, s0, 9
	s_add_i32 s0, s0, s1
	s_mulk_i32 s0, 0x330
	s_sub_i32 s0, s2, s0
	s_sext_i32_i16 s1, s0
	s_bfe_u32 s1, s1, 0x3001c
	s_add_i32 s1, s0, s1
	s_sext_i32_i16 s3, s1
	s_and_b32 s1, s1, 0xfff8
	s_ashr_i32 s6, s3, 3
	s_sub_i32 s8, s0, s1
	s_sub_i32 s80, s94, 48
	s_sub_i32 s0, s2, 48
	s_cmp_gt_u32 s2, 47
	s_cselect_b32 s81, s0, 0x10000000
	s_cmpk_lt_i32 s81, 0x198
	s_cselect_b64 s[0:1], -1, 0
	v_writelane_b32 v245, s0, 3
	s_waitcnt lgkmcnt(0)
	v_mov_b32_e32 v0, 0xe0
	v_sub_co_u32_e32 v0, vcc, s2, v0
	v_writelane_b32 v245, s1, 4
	s_mul_hi_i32 s0, s81, 0xa0a0a0a1
	s_add_i32 s0, s0, s81
	s_lshr_b32 s1, s0, 31
	s_lshr_b32 s0, s0, 8
	s_add_i32 s0, s0, s1
	s_mulk_i32 s0, 0x198
	s_sub_i32 s0, s81, s0
	s_sext_i32_i16 s1, s0
	s_bfe_u32 s1, s1, 0x3001c
	s_add_i32 s1, s0, s1
	s_sext_i32_i16 s3, s1
	s_and_b32 s1, s1, 0xfff8
	s_ashr_i32 s5, s3, 3
	s_sub_i32 s7, s0, s1
	s_cmpk_lt_i32 s2, 0x110
	s_cselect_b64 s[0:1], -1, 0
	v_writelane_b32 v245, s0, 5
	s_bfe_u32 s87, s2, 0x50002
	s_lshr_b32 s3, s2, 2
	v_writelane_b32 v245, s1, 6
	s_and_b32 s0, s2, 3
	s_lshl_b32 s89, s87, 6
	s_lshl_b32 s1, s0, 2
	s_lshl_b32 s0, s0, 8
	s_cmp_lg_u32 s87, 0
	v_writelane_b32 v245, s1, 7
	s_cselect_b64 s[36:37], -1, 0
	s_cmp_eq_u32 s87, 31
	v_writelane_b32 v245, s0, 8
	s_cselect_b64 s[38:39], -1, 0
	s_lshl_b32 s0, s2, 8
	s_and_b32 s0, s0, 0x300
	s_cmp_eq_u32 s87, 0
	v_writelane_b32 v245, s0, 9
	s_cselect_b64 s[0:1], -1, 0
	v_writelane_b32 v245, s0, 10
	s_cmp_gt_u32 s87, 1
	s_movk_i32 s93, 0x67
	v_writelane_b32 v245, s1, 11
	s_cselect_b64 s[0:1], -1, 0
	v_writelane_b32 v245, s0, 12
	s_cmp_gt_u32 s87, 2
	v_mov_b32_e32 v185, 0
	v_writelane_b32 v245, s1, 13
	s_cselect_b64 s[0:1], -1, 0
	v_writelane_b32 v245, s0, 14
	s_cmp_gt_u32 s87, 3
	v_mov_b32_e32 v216, 0x358637bd
	v_writelane_b32 v245, s1, 15
	s_cselect_b64 s[0:1], -1, 0
	v_writelane_b32 v245, s0, 16
	s_cmp_gt_u32 s87, 4
	v_mov_b32_e32 v217, 0x1000
	v_writelane_b32 v245, s1, 17
	s_cselect_b64 s[0:1], -1, 0
	v_writelane_b32 v245, s0, 18
	s_cmp_gt_u32 s87, 5
	v_mov_b32_e32 v218, 0x2000
	v_writelane_b32 v245, s1, 19
	s_cselect_b64 s[0:1], -1, 0
	v_writelane_b32 v245, s0, 20
	s_cmp_gt_u32 s87, 6
	v_mov_b32_e32 v219, 0x11083000
	v_writelane_b32 v245, s1, 21
	s_cselect_b64 s[0:1], -1, 0
	v_writelane_b32 v245, s0, 22
	s_cmp_gt_u32 s87, 7
	v_mov_b32_e32 v220, 1
	v_writelane_b32 v245, s1, 23
	s_cselect_b64 s[0:1], -1, 0
	v_writelane_b32 v245, s0, 24
	s_cmp_gt_u32 s87, 8
	v_mov_b32_e32 v222, 0x3000
	v_writelane_b32 v245, s1, 25
	s_cselect_b64 s[0:1], -1, 0
	s_cmp_gt_u32 s87, 9
	s_cselect_b64 s[40:41], -1, 0
	s_cmp_gt_u32 s87, 10
	s_cselect_b64 s[42:43], -1, 0
	s_cmp_gt_u32 s87, 11
	s_cselect_b64 s[44:45], -1, 0
	s_cmp_gt_u32 s87, 12
	s_cselect_b64 s[46:47], -1, 0
	s_cmp_gt_u32 s87, 13
	v_writelane_b32 v245, s0, 26
	s_cselect_b64 s[48:49], -1, 0
	s_cmp_gt_u32 s87, 14
	v_writelane_b32 v245, s1, 27
	s_cselect_b64 s[0:1], -1, 0
	v_writelane_b32 v245, s0, 28
	s_cmp_gt_u32 s87, 15
	v_mov_b32_e32 v223, 0x2200
	v_writelane_b32 v245, s1, 29
	s_cselect_b64 s[0:1], -1, 0
	v_writelane_b32 v245, s0, 30
	s_cmp_gt_u32 s87, 16
	s_movk_i32 s90, 0x4000
	v_writelane_b32 v245, s1, 31
	s_cselect_b64 s[0:1], -1, 0
	v_writelane_b32 v245, s0, 32
	s_cmp_gt_u32 s87, 17
	s_movk_i32 s68, 0x4800
	v_writelane_b32 v245, s1, 33
	s_cselect_b64 s[0:1], -1, 0
	v_writelane_b32 v245, s0, 34
	s_cmp_gt_u32 s87, 18
	s_mov_b32 s69, 0xffff0000
	v_writelane_b32 v245, s1, 35
	s_cselect_b64 s[0:1], -1, 0
	v_writelane_b32 v245, s0, 36
	s_cmp_gt_u32 s87, 19
	s_movk_i32 s50, 0x3000
	v_writelane_b32 v245, s1, 37
	s_cselect_b64 s[0:1], -1, 0
	v_writelane_b32 v245, s0, 38
	s_cmp_gt_u32 s87, 20
	s_mov_b32 s52, 0
	v_writelane_b32 v245, s1, 39
	s_cselect_b64 s[0:1], -1, 0
	v_writelane_b32 v245, s0, 40
	s_cmp_gt_u32 s87, 21
	s_mov_b32 s97, 0
	v_writelane_b32 v245, s1, 41
	s_cselect_b64 s[0:1], -1, 0
	v_writelane_b32 v245, s0, 42
	s_cmp_gt_u32 s87, 22
	s_nop 0
	v_writelane_b32 v245, s1, 43
	s_cselect_b64 s[0:1], -1, 0
	v_writelane_b32 v245, s0, 44
	s_cmp_gt_u32 s87, 23
	s_barrier
	v_writelane_b32 v245, s1, 45
	s_cselect_b64 s[0:1], -1, 0
	v_writelane_b32 v245, s0, 46
	s_cmp_gt_u32 s87, 24
	s_nop 0
	v_writelane_b32 v245, s1, 47
	s_cselect_b64 s[0:1], -1, 0
	v_writelane_b32 v245, s0, 48
	s_cmp_gt_u32 s87, 25
	s_nop 0
	v_writelane_b32 v245, s1, 49
	s_cselect_b64 s[0:1], -1, 0
	v_writelane_b32 v245, s0, 50
	s_cmp_gt_u32 s87, 26
	s_nop 0
	v_writelane_b32 v245, s1, 51
	s_cselect_b64 s[0:1], -1, 0
	v_writelane_b32 v245, s0, 52
	s_cmp_gt_u32 s87, 27
	s_nop 0
	v_writelane_b32 v245, s1, 53
	s_cselect_b64 s[0:1], -1, 0
	v_writelane_b32 v245, s0, 54
	s_cmp_gt_u32 s87, 28
	s_nop 0
	v_writelane_b32 v245, s1, 55
	s_cselect_b64 s[0:1], -1, 0
	v_writelane_b32 v245, s0, 56
	s_cmp_gt_u32 s87, 29
	s_nop 0
	v_writelane_b32 v245, s1, 57
	s_cselect_b64 s[0:1], -1, 0
	v_writelane_b32 v245, s0, 58
	s_nop 1
	v_writelane_b32 v245, s1, 59
	v_sub_co_u32_e64 v214, s[0:1], s2, 32
	s_xor_b64 s[0:1], s[0:1], -1
	s_nop 0
	v_writelane_b32 v245, s0, 60
	s_nop 1
	v_writelane_b32 v245, s1, 61
	s_sub_i32 s0, s94, 32
	v_writelane_b32 v245, s0, 62
	s_lshl_b32 s0, s3, 6
	s_addk_i32 s0, 0x2000
	v_writelane_b32 v245, s0, 63
	s_lshl_b32 s0, s3, 3
	s_cmpk_lt_i32 s2, 0x198
	v_writelane_b32 v244, s0, 0
	s_mul_hi_i32 s0, s2, 0x78787879
	s_cselect_b64 s[10:11], -1, 0
	v_writelane_b32 v244, s10, 1
	s_lshr_b32 s1, s0, 31
	s_ashr_i32 s0, s0, 6
	v_writelane_b32 v244, s11, 2
	s_add_i32 s10, s0, s1
	s_mul_i32 s0, s10, 0x88
	s_sub_i32 s0, s2, s0
	s_bfe_u32 s1, s0, 0x3001c
	s_add_i32 s1, s0, s1
	s_and_b32 s3, s1, 0xfff8
	s_sub_i32 s9, s0, s3
	s_sext_i32_i16 s0, s1
	s_ashr_i32 s11, s10, 31
	s_ashr_i32 s14, s0, 3
	s_lshl_b64 s[0:1], s[10:11], 11
	v_writelane_b32 v244, s0, 3
	s_nop 1
	v_writelane_b32 v244, s1, 4
	s_mov_b32 s0, s10
	v_writelane_b32 v244, s0, 5
	s_nop 1
	v_writelane_b32 v244, s1, 6
	s_lshl_b64 s[0:1], s[10:11], 21
	v_writelane_b32 v244, s0, 7
	s_cmpk_lt_i32 s2, 0x88
	s_nop 0
	v_writelane_b32 v244, s1, 8
	s_cselect_b64 s[0:1], -1, 0
	v_writelane_b32 v244, s0, 9
	s_cmpk_gt_u32 s2, 0x87
	s_nop 0
	v_writelane_b32 v244, s1, 10
	s_cselect_b64 s[0:1], -1, 0
	v_writelane_b32 v244, s0, 11
	s_nop 1
	v_writelane_b32 v244, s1, 12
	s_add_i32 s0, s84, 0xfffffbc0
	v_writelane_b32 v244, s0, 13
	s_add_i32 s0, s88, 0xfffffbc0
	s_cmpk_lt_i32 s2, 0x200
	v_writelane_b32 v244, s0, 14
	s_cselect_b64 s[0:1], -1, 0
	v_writelane_b32 v244, s0, 15
	s_ashr_i32 s3, s2, 31
	s_and_b32 s12, s2, 15
	v_writelane_b32 v244, s1, 16
	s_lshr_b32 s0, s3, 23
	s_add_i32 s0, s2, s0
	s_and_b32 s0, s0, 0xfe00
	s_sub_i32 s0, s2, s0
	s_sext_i32_i16 s1, s0
	s_bfe_u32 s1, s1, 0x3001c
	s_add_i32 s1, s0, s1
	s_and_b32 s4, s1, 0xfff8
	s_sub_i32 s15, s0, s4
	s_sext_i32_i16 s0, s1
	s_ashr_i32 s16, s0, 3
	v_readfirstlane_b32 s0, v0
	s_ashr_i32 s4, s0, 4
	s_add_i32 s10, s4, 32
	s_lshl_b32 s0, s4, 5
	s_ashr_i32 s11, s10, 31
	s_lshl_b32 s13, s12, 19
	s_ashr_i32 s1, s0, 31
	s_lshl_b32 s17, s15, 6
	v_writelane_b32 v244, s13, 17
	s_lshl_b64 s[18:19], s[10:11], 19
	v_writelane_b32 v244, s18, 18
	s_cmp_gt_i32 s4, -1
	s_nop 0
	v_writelane_b32 v244, s19, 19
	s_cselect_b64 s[18:19], -1, 0
	v_writelane_b32 v244, s18, 20
	s_ashr_i32 s11, s10, 3
	s_lshl_b32 s13, s10, 8
	v_writelane_b32 v244, s19, 21
	v_writelane_b32 v244, s11, 22
	s_lshl_b32 s10, s12, 8
	v_writelane_b32 v244, s10, 23
	s_and_b32 s56, s2, 7
	s_mul_i32 s56, s56, 28
	s_lshr_b32 s57, s2, 3
	s_add_i32 s56, s56, s57
	s_cmpk_lt_u32 s2, 0xe0
	s_cselect_b32 s54, s56, s2
	s_mov_b32 s55, 0
	s_lshl_b32 s10, s54, 4
	s_add_i32 s11, s10, 0x1200
	s_mul_i32 s10, s54, 36
	s_add_i32 s18, s10, 0x80
	s_or_b32 s10, s13, 0x80
	v_writelane_b32 v244, s10, 24
	s_or_b32 s10, s13, 0x90
	v_writelane_b32 v244, s10, 25
	s_or_b32 s10, s13, 0xa0
	v_writelane_b32 v244, s10, 26
	v_writelane_b32 v244, s13, 27
	s_or_b32 s10, s13, 0xb0
	v_writelane_b32 v244, s10, 28
	s_add_i32 s10, s54, 1
	s_cmpk_lt_u32 s10, 0xe0
	s_cselect_b32 s12, 36, 16
	s_cmp_gt_i32 s54, 62
	s_cselect_b32 s19, s12, 38
	s_add_i32 s12, s54, 2
	s_cmpk_lt_u32 s12, 0xe0
	s_cselect_b32 s12, 36, 16
	s_cmp_gt_i32 s54, 61
	s_cselect_b32 s12, s12, 38
	s_add_i32 s20, s19, s12
	s_cmpk_gt_u32 s2, 0xdf
	s_cselect_b64 s[12:13], -1, 0
	v_writelane_b32 v244, s12, 29
	s_nop 1
	v_writelane_b32 v244, s13, 30
	s_and_b64 s[12:13], s[12:13], exec
	s_cselect_b32 s21, 16, 36
	s_cselect_b32 s22, s11, s18
	s_and_b64 s[12:13], vcc, exec
	s_cselect_b32 s11, s18, s11
	s_cmp_lt_i32 s54, 64
	s_mul_i32 s12, s54, 38
	s_cselect_b32 s13, s12, s22
	s_cselect_b32 s18, s12, s11
	s_cselect_b32 s21, 38, s21
	s_and_b32 s12, s13, 62
	s_ashr_i32 s11, s13, 6
	s_sub_i32 s12, 64, s12
	s_cmp_lt_u32 s12, s21
	v_mov_b32_e32 v0, s12
	s_cselect_b64 s[12:13], -1, 0
	v_sub_u32_e64 v0, s21, v0 clamp
	v_writelane_b32 v244, s12, 31
	s_add_i32 s11, s11, 1
	s_lshr_b32 s56, s11, 5
	s_and_b32 s57, s11, 3
	s_cmpk_lt_u32 s11, 0x80
	s_cselect_b32 s28, s56, s57
	v_writelane_b32 v244, s13, 32
	s_and_b32 s56, s11, 31
	s_ashr_i32 s57, s11, 2
	s_cmpk_lt_u32 s11, 0x80
	s_cselect_b32 s92, s56, s57
	v_readfirstlane_b32 s11, v0
	s_nop 1
	v_writelane_b32 v244, s11, 33
	s_sub_i32 s11, 64, s11
	s_cmp_gt_u32 s11, s19
	s_cselect_b32 s22, 2, 1
	s_cmp_gt_u32 s11, s20
	s_cselect_b64 s[12:13], -1, 0
	s_cmp_lg_u64 s[12:13], 0
	s_addc_u32 s11, s22, 0
	v_writelane_b32 v244, s11, 34
	s_ashr_i32 s11, s10, 31
	s_lshl_b64 s[10:11], s[10:11], 17
	v_writelane_b32 v244, s10, 35
	s_lshl_b64 s[12:13], s[54:55], 17
	s_nop 0
	v_writelane_b32 v244, s11, 36
	s_sext_i32_i16 s10, s8
	s_cmp_lt_i32 s10, 0
	s_cselect_b32 s10, s93, 0x66
	s_mul_i32 s8, s10, s8
	s_add_i32 s8, s8, s6
	s_sext_i32_i16 s6, s8
	s_mulk_i32 s6, 0x2aab
	s_lshr_b32 s10, s6, 31
	s_ashr_i32 s6, s6, 21
	s_add_i32 s6, s6, s10
	s_mul_i32 s10, s6, 0xc0
	s_sext_i32_i16 s6, s6
	s_lshl_b32 s11, s6, 3
	v_writelane_b32 v244, s12, 37
	s_sub_i32 s6, 34, s11
	s_sub_i32 s10, s8, s10
	v_writelane_b32 v244, s13, 38
	s_min_u32 s12, s6, 8
	s_sext_i32_i16 s6, s7
	s_cmp_lt_i32 s6, 0
	s_cselect_b32 s6, 52, 51
	s_mul_i32 s6, s6, s7
	s_add_i32 s6, s6, s5
	s_sext_i32_i16 s5, s6
	s_mulk_i32 s5, 0x2aab
	s_lshr_b32 s7, s5, 31
	s_ashr_i32 s5, s5, 20
	s_add_i32 s5, s5, s7
	s_mul_i32 s7, s5, 0x60
	s_sext_i32_i16 s5, s5
	s_lshl_b32 s5, s5, 3
	s_sub_i32 s13, s6, s7
	s_sub_i32 s6, 34, s5
	s_min_u32 s22, s6, 8
	s_sext_i32_i16 s6, s9
	s_cmp_lt_i32 s6, 0
	s_cselect_b32 s6, 18, 17
	s_mul_i32 s6, s6, s9
	s_add_i32 s6, s6, s14
	s_sext_i32_i16 s7, s6
	s_bfe_u32 s7, s7, 0x5001a
	s_add_i32 s7, s6, s7
	s_and_b32 s8, s7, 0xffe0
	s_sub_i32 s14, s6, s8
	s_sext_i32_i16 s6, s7
	s_ashr_i32 s6, s6, 5
	s_lshl_b32 s23, s6, 3
	s_sub_i32 s6, 34, s23
	s_min_u32 s24, s6, 8
	s_sext_i32_i16 s6, s15
	s_cmp_lt_i32 s6, 0
	s_mulk_i32 s15, 0x41
	s_cselect_b32 s6, s15, s17
	s_add_i32 s6, s6, s16
	s_sext_i32_i16 s7, s6
	s_bfe_u32 s7, s7, 0x70018
	s_add_i32 s7, s6, s7
	s_and_b32 s8, s7, 0xff80
	s_sub_i32 s6, s6, s8
	s_bfe_i32 s8, s6, 0x80000
	s_bfe_u32 s8, s8, 0x3000c
	s_add_i32 s8, s6, s8
	s_and_b32 s9, s8, 0xf8
	s_sext_i32_i16 s7, s7
	s_sub_i32 s6, s6, s9
	s_and_b32 s15, s18, 62
	s_ashr_i32 s7, s7, 7
	s_bfe_i32 s8, s8, 0x80000
	s_sub_i32 s9, 64, s15
	s_lshl_b32 s7, s7, 3
	s_sext_i32_i16 s8, s8
	s_sext_i32_i8 s6, s6
	s_min_u32 s9, s9, s21
	s_add_i32 s30, s7, s6
	s_ashr_i32 s6, s8, 3
	v_writelane_b32 v244, s6, 39
	s_lshr_b32 s6, s8, 3
	s_lshr_b32 s56, s18, 6
	s_lshr_b32 s57, s56, 5
	s_and_b32 s58, s56, 3
	s_and_b32 s59, s56, 31
	s_ashr_i32 s18, s18, 8
	s_cmpk_lt_u32 s56, 0x80
	s_cselect_b32 s17, s57, s58
	s_cselect_b32 s18, s59, s18
	s_sub_i32 s7, 64, s9
	s_cmp_gt_u32 s7, s19
	s_cselect_b32 s16, 2, 1
	s_cmp_gt_u32 s7, s20
	v_writelane_b32 v244, s9, 40
	s_cselect_b64 s[8:9], -1, 0
	s_cmp_lg_u64 s[8:9], 0
	s_addc_u32 s8, s16, 0
	s_bfe_i64 s[6:7], s[6:7], 0x100000
	s_lshl_b64 s[6:7], s[6:7], 19
	v_writelane_b32 v244, s6, 41
	s_ashr_i32 s19, s18, 31
	s_ashr_i32 s31, s30, 31
	v_writelane_b32 v244, s7, 42
	s_lshl_b32 s6, s15, 7
	v_writelane_b32 v244, s6, 43
	v_writelane_b32 v244, s17, 44
	s_lshl_b32 s6, s17, 21
	v_writelane_b32 v244, s6, 45
	s_mov_b32 s6, s18
	v_writelane_b32 v244, s6, 46
	v_cvt_f32_ubyte0_e32 v1, s12
	v_rcp_iflag_f32_e32 v2, v1
	v_writelane_b32 v244, s7, 47
	s_lshl_b64 s[6:7], s[18:19], 21
	v_writelane_b32 v244, s6, 48
	s_nop 1
	v_writelane_b32 v244, s7, 49
	s_mov_b32 s6, s30
	v_writelane_b32 v244, s6, 50
	s_nop 1
	v_writelane_b32 v244, s7, 51
	s_lshl_b64 s[6:7], s[30:31], 19
	v_writelane_b32 v244, s6, 52
	s_cmp_eq_u32 s15, 0
	s_nop 0
	v_writelane_b32 v244, s7, 53
	s_cselect_b32 s6, s8, 0
	v_writelane_b32 v244, s6, 54
	s_sext_i32_i16 s6, s10
	v_cvt_f32_i32_e32 v0, s6
	s_cselect_b32 s7, 2, 1
	s_ashr_i32 s6, s6, 30
	v_writelane_b32 v244, s7, 55
	v_mul_f32_e32 v2, v0, v2
	v_trunc_f32_e32 v2, v2
	v_fma_f32 v0, -v2, v1, v0
	s_or_b32 s8, s6, 1
	v_cmp_ge_f32_e64 s[6:7], |v0|, v1
	v_cvt_i32_f32_e32 v0, v2
	s_and_b64 s[6:7], s[6:7], exec
	s_cselect_b32 s6, s8, 0
	v_cvt_f32_ubyte0_e32 v1, s22
	v_readfirstlane_b32 s7, v0
	s_add_i32 s15, s7, s6
	s_mul_i32 s6, s15, s12
	s_sub_i32 s6, s10, s6
	s_sext_i32_i16 s6, s6
	s_add_i32 s6, s11, s6
	v_writelane_b32 v244, s6, 56
	s_sext_i32_i16 s6, s13
	v_cvt_f32_i32_e32 v0, s6
	v_rcp_iflag_f32_e32 v2, v1
	s_ashr_i32 s6, s6, 30
	s_or_b32 s8, s6, 1
	v_mul_f32_e32 v2, v0, v2
	v_trunc_f32_e32 v2, v2
	v_fma_f32 v0, -v2, v1, v0
	v_cmp_ge_f32_e64 s[6:7], |v0|, v1
	v_cvt_i32_f32_e32 v0, v2
	s_and_b64 s[6:7], s[6:7], exec
	s_cselect_b32 s6, s8, 0
	v_cvt_f32_ubyte0_e32 v1, s24
	v_readfirstlane_b32 s7, v0
	s_add_i32 s6, s7, s6
	s_mul_i32 s7, s6, s22
	s_sub_i32 s7, s13, s7
	s_sext_i32_i8 s7, s7
	s_add_i32 s10, s5, s7
	s_sext_i32_i16 s5, s14
	v_cvt_f32_i32_e32 v0, s5
	v_rcp_iflag_f32_e32 v2, v1
	s_bfe_i64 s[8:9], s[6:7], 0x80000
	s_lshl_b64 s[8:9], s[8:9], 18
	v_writelane_b32 v244, s8, 57
	s_ashr_i32 s11, s10, 31
	v_mul_f32_e32 v2, v0, v2
	v_writelane_b32 v244, s9, 58
	s_mov_b32 s8, s10
	v_writelane_b32 v244, s8, 59
	v_trunc_f32_e32 v2, v2
	v_fma_f32 v0, -v2, v1, v0
	v_writelane_b32 v244, s9, 60
	s_lshl_b64 s[8:9], s[10:11], 18
	v_writelane_b32 v244, s8, 61
	s_ashr_i32 s5, s5, 30
	s_or_b32 s5, s5, 1
	v_writelane_b32 v244, s9, 62
	v_cmp_ge_f32_e64 s[8:9], |v0|, v1
	v_cvt_i32_f32_e32 v0, v2
	s_and_b64 s[8:9], s[8:9], exec
	v_writelane_b32 v244, s26, 63
	s_sext_i32_i8 s6, s6
	s_cselect_b32 s5, s5, 0
	v_writelane_b32 v243, s27, 0
	v_writelane_b32 v243, s6, 1
	v_readfirstlane_b32 s6, v0
	s_add_i32 s6, s6, s5
	s_mul_i32 s5, s6, s24
	s_sub_i32 s5, s14, s5
	s_sext_i32_i8 s5, s5
	s_add_i32 s5, s23, s5
	s_mul_i32 s7, s95, s94
	v_writelane_b32 v243, s5, 2
	s_sext_i32_i16 s5, s15
	s_mul_i32 s95, s7, s33
	v_writelane_b32 v243, s5, 3
	s_sext_i32_i8 s5, s6
	s_bfe_i64 s[6:7], s[6:7], 0x80000
	v_writelane_b32 v243, s5, 4
	s_lshl_b64 s[6:7], s[6:7], 19
	v_writelane_b32 v243, s6, 5
	s_ashr_i32 s5, s4, 31
	s_lshl_b64 s[4:5], s[4:5], 19
	v_writelane_b32 v243, s7, 6
	v_writelane_b32 v243, s4, 7
	s_lshl_b64 s[0:1], s[0:1], 2
	s_ashr_i32 s85, s84, 31
	v_writelane_b32 v243, s5, 8
	v_writelane_b32 v243, s0, 9
	s_lshl_b32 s4, s94, 5
	v_mbcnt_lo_u32_b32 v0, -1, 0
	v_writelane_b32 v243, s1, 10
	v_writelane_b32 v243, s84, 11
	s_add_i32 s1, s84, 0xfffff800
	s_movk_i32 s0, 0x110
	v_writelane_b32 v243, s85, 12
	v_writelane_b32 v243, s1, 13
	s_lshl_b32 s1, s2, 5
	v_writelane_b32 v243, s1, 14
	s_addk_i32 s1, 0xdc00
	v_writelane_b32 v243, s1, 15
	v_writelane_b32 v243, s4, 16
	s_add_i32 s1, s4, 0xfffffc00
	v_writelane_b32 v243, s1, 17
	s_lshl_b32 s1, s94, 10
	v_writelane_b32 v243, s1, 18
	s_lshl_b32 s1, s2, 12
	v_writelane_b32 v243, s1, 19
	s_lshl_b32 s1, s94, 14
	v_writelane_b32 v243, s1, 20
	s_add_i32 s1, 0, 0x20000
	v_writelane_b32 v243, s1, 21
	s_add_i32 s1, 0, 0x20004
	v_writelane_b32 v243, s1, 22
	v_cmp_gt_i32_e64 s[0:1], s0, v214
	v_cndmask_b32_e64 v215, 0, 1, s[26:27]
	v_mbcnt_hi_u32_b32 v221, -1, v0
	v_writelane_b32 v243, s0, 23
	s_movk_i32 s33, 0x2000
	s_mov_b32 s84, s28
	v_writelane_b32 v243, s1, 24
	v_cmp_gt_u32_e64 s[0:1], 64, v195
	s_mov_b64 s[4:5], 0x80
	s_nop 0
	v_writelane_b32 v243, s0, 25
	s_nop 1
	v_writelane_b32 v243, s1, 26
	s_lshl_b64 s[0:1], s[54:55], 2
	v_writelane_b32 v243, s0, 27
	s_nop 1
	v_writelane_b32 v243, s1, 28
	v_writelane_b32 v243, s36, 29
	s_nop 1
	v_writelane_b32 v243, s37, 30
	v_writelane_b32 v243, s38, 31
	s_nop 1
	v_writelane_b32 v243, s39, 32
	v_writelane_b32 v243, s40, 33
	s_nop 1
	v_writelane_b32 v243, s41, 34
	v_writelane_b32 v243, s42, 35
	s_nop 1
	v_writelane_b32 v243, s43, 36
	v_writelane_b32 v243, s44, 37
	s_nop 1
	v_writelane_b32 v243, s45, 38
	v_writelane_b32 v243, s46, 39
	s_nop 1
	v_writelane_b32 v243, s47, 40
	v_writelane_b32 v243, s48, 41
	s_nop 1
	v_writelane_b32 v243, s49, 42
	v_writelane_b32 v243, s94, 43
	s_nop 1
	v_writelane_b32 v243, s95, 44
	v_writelane_b32 v243, s82, 45
	s_nop 1
	v_writelane_b32 v243, s83, 46
	v_writelane_b32 v243, s86, 47
	v_writelane_b32 v243, s80, 48
	v_writelane_b32 v243, s81, 49
	v_writelane_b32 v243, s87, 50
	v_writelane_b32 v243, s89, 51
	v_writelane_b32 v243, s95, 52
	s_branch .LBB0_414
